# attention: hand-scheduled path also for the first computed tile of each wave (own key chunk, abs-distance bias)
# speedup vs baseline: 1.0140x; 1.0015x over previous
.LBB0_961:
	s_mov_b32 s14, s13
	s_add_i32 s13, s14, 1
	s_cmp_lt_i32 s14, s12
	s_cbranch_scc1 .Latt_ctl_orig
	s_cmp_eq_u32 s14, s78
	s_cbranch_scc1 .Latt_ctl_orig
	s_cmp_eq_u32 s14, s12
	s_cbranch_scc1 .Latt_first
	s_branch .Latt_fast

.Latt_first:
	s_and_b32 s15, s9, 0x4000
	s_max_i32 s20, s73, 0
	v_or_b32_e32 v246, s15, v220
	v_xor_b32_e32 v250, 0x80, v246
	v_xor_b32_e32 v247, 32, v246
	v_xor_b32_e32 v248, 64, v246
	s_sub_i32 s38, s73, 64
	s_max_i32 s74, s38, 0
	s_lshl_b64 s[16:17], s[74:75], 12
	s_add_i32 s38, s9, 0x4000
	s_and_b32 s38, s38, 0x4000
	s_add_i32 s39, s38, s10
	s_add_i32 s40, s39, 0x400
	s_add_i32 s41, s38, s11
	s_add_i32 s42, s41, 0x400
	s_mov_b64 s[44:45], 0x10000
	s_mov_b32 s43, m0
	ds_read_b128 v[180:183], v250
	ds_read_b128 v[184:187], v219 offset:4096
	ds_read_b128 v[188:191], v246
	ds_read_b128 v[192:195], v219
	ds_read_b128 v[200:203], v247
	ds_read_b128 v[204:207], v219 offset:1024
	ds_read_b128 v[208:211], v248
	ds_read_b128 v[212:215], v219 offset:2048
	v_lshl_add_u64 v[132:133], v[172:173], 0, s[16:17]
	s_mov_b32 m0, s39
	s_nop 0
	global_load_lds_dwordx4 v[132:133], off
	v_lshl_add_u64 v[132:133], v[132:133], 0, v[66:67]
	s_mov_b32 m0, s40
	s_nop 0
	global_load_lds_dwordx4 v[132:133], off
	v_lshl_add_u64 v[134:135], v[168:169], 0, s[16:17]
	s_mov_b32 m0, s41
	s_nop 0
	global_load_lds_dwordx4 v[134:135], off
	v_lshl_add_u64 v[134:135], v[134:135], 0, s[44:45]
	s_mov_b32 m0, s42
	s_nop 0
	global_load_lds_dwordx4 v[134:135], off
	s_mov_b32 m0, s43
	v_add_u32_e32 v148, s20, v216
	v_sub_u32_e32 v148, v148, v166
	v_cvt_f32_i32_e32 v148, v148
	v_mul_f32_e32 v148, v164, v148
	v_add_f32_e32 v149, v164, v148
	v_add_f32_e32 v150, v164, v149
	v_add_f32_e32 v151, v164, v150
	v_add_f32_e32 v152, v223, v151
	v_add_f32_e32 v153, v164, v152
	v_add_f32_e32 v154, v164, v153
	v_add_f32_e32 v155, v164, v154
	v_add_f32_e32 v156, v223, v155
	v_add_f32_e32 v157, v164, v156
	v_add_f32_e32 v158, v164, v157
	v_add_f32_e32 v159, v164, v158
	v_add_f32_e32 v160, v223, v159
	v_add_f32_e32 v161, v164, v160
	v_add_f32_e32 v162, v164, v161
	v_add_f32_e32 v163, v164, v162
	v_sub_f32_e64 v148, -|v148|, v221
	v_sub_f32_e64 v149, -|v149|, v221
	v_sub_f32_e64 v150, -|v150|, v221
	v_sub_f32_e64 v151, -|v151|, v221
	v_sub_f32_e64 v152, -|v152|, v221
	v_sub_f32_e64 v153, -|v153|, v221
	v_sub_f32_e64 v154, -|v154|, v221
	v_sub_f32_e64 v155, -|v155|, v221
	v_sub_f32_e64 v156, -|v156|, v221
	v_sub_f32_e64 v157, -|v157|, v221
	v_sub_f32_e64 v158, -|v158|, v221
	v_sub_f32_e64 v159, -|v159|, v221
	v_sub_f32_e64 v160, -|v160|, v221
	v_sub_f32_e64 v161, -|v161|, v221
	v_sub_f32_e64 v162, -|v162|, v221
	v_sub_f32_e64 v163, -|v163|, v221
	v_xor_b32_e32 v249, 0x60, v246
	v_xor_b32_e32 v251, 0xa0, v246
	v_xor_b32_e32 v252, 0xc0, v246
	v_xor_b32_e32 v253, 0xe0, v246
	v_add_u32_e32 v228, s15, v222
	s_waitcnt lgkmcnt(6)
	v_mfma_f32_32x32x16_bf16 v[132:147], v[180:183], v[184:187], v[148:163]
	ds_read_b128 v[180:183], v249
	ds_read_b128 v[184:187], v219 offset:3072
	s_waitcnt lgkmcnt(6)
	v_mfma_f32_32x32x16_bf16 v[148:163], v[188:191], v[192:195], v[148:163]
	ds_read_b128 v[188:191], v251
	ds_read_b128 v[192:195], v219 offset:5120
	s_waitcnt lgkmcnt(6)
	v_mfma_f32_32x32x16_bf16 v[148:163], v[200:203], v[204:207], v[148:163]
	ds_read_b128 v[200:203], v252
	ds_read_b128 v[204:207], v219 offset:6144
	s_waitcnt lgkmcnt(6)
	v_mfma_f32_32x32x16_bf16 v[148:163], v[208:211], v[212:215], v[148:163]
	ds_read_b128 v[208:211], v253
	ds_read_b128 v[212:215], v219 offset:7168
	s_waitcnt lgkmcnt(6)
	v_mfma_f32_32x32x16_bf16 v[148:163], v[180:183], v[184:187], v[148:163]
	ds_read_b64_tr_b16 v[180:181], v228 offset:32768
	ds_read_b64_tr_b16 v[182:183], v228 offset:33280
	ds_read_b64_tr_b16 v[184:185], v228 offset:33792
	ds_read_b64_tr_b16 v[186:187], v228 offset:34304
	s_waitcnt lgkmcnt(8)
	v_mfma_f32_32x32x16_bf16 v[132:147], v[188:191], v[192:195], v[132:147]
	ds_read_b64_tr_b16 v[188:189], v228 offset:36864
	ds_read_b64_tr_b16 v[190:191], v228 offset:37376
	ds_read_b64_tr_b16 v[192:193], v228 offset:37888
	ds_read_b64_tr_b16 v[194:195], v228 offset:38400
	s_waitcnt lgkmcnt(10)
	v_mfma_f32_32x32x16_bf16 v[132:147], v[200:203], v[204:207], v[132:147]
	ds_read_b64_tr_b16 v[200:201], v228 offset:40960
	ds_read_b64_tr_b16 v[202:203], v228 offset:41472
	ds_read_b64_tr_b16 v[204:205], v228 offset:41984
	ds_read_b64_tr_b16 v[206:207], v228 offset:42496
	s_waitcnt lgkmcnt(12)
	v_mfma_f32_32x32x16_bf16 v[132:147], v[208:211], v[212:215], v[132:147]
	ds_read_b64_tr_b16 v[208:209], v228 offset:45056
	ds_read_b64_tr_b16 v[210:211], v228 offset:45568
	v_exp_f32_e32 v148, v148
	v_exp_f32_e32 v149, v149
	v_exp_f32_e32 v150, v150
	v_exp_f32_e32 v151, v151
	v_exp_f32_e32 v152, v152
	v_exp_f32_e32 v153, v153
	v_exp_f32_e32 v154, v154
	v_exp_f32_e32 v155, v155
	v_exp_f32_e32 v156, v156
	v_exp_f32_e32 v157, v157
	v_exp_f32_e32 v158, v158
	v_exp_f32_e32 v159, v159
	v_exp_f32_e32 v160, v160
	v_exp_f32_e32 v161, v161
	v_exp_f32_e32 v162, v162
	v_exp_f32_e32 v163, v163
	v_add_f32_e32 v170, v170, v148
	v_add_f32_e32 v171, v171, v149
	v_cvt_pk_bf16_f32 v230, v148, v149
	v_add_f32_e32 v170, v170, v150
	v_add_f32_e32 v171, v171, v151
	v_cvt_pk_bf16_f32 v231, v150, v151
	v_add_f32_e32 v170, v170, v152
	v_add_f32_e32 v171, v171, v153
	v_cvt_pk_bf16_f32 v232, v152, v153
	v_add_f32_e32 v170, v170, v154
	v_add_f32_e32 v171, v171, v155
	v_cvt_pk_bf16_f32 v233, v154, v155
	v_add_f32_e32 v170, v170, v156
	v_add_f32_e32 v171, v171, v157
	v_cvt_pk_bf16_f32 v234, v156, v157
	v_add_f32_e32 v170, v170, v158
	v_add_f32_e32 v171, v171, v159
	v_cvt_pk_bf16_f32 v235, v158, v159
	v_add_f32_e32 v170, v170, v160
	v_add_f32_e32 v171, v171, v161
	v_cvt_pk_bf16_f32 v236, v160, v161
	v_add_f32_e32 v170, v170, v162
	v_add_f32_e32 v171, v171, v163
	v_cvt_pk_bf16_f32 v237, v162, v163
	s_waitcnt lgkmcnt(12)
	ds_read_b64_tr_b16 v[212:213], v228 offset:46080
	ds_read_b64_tr_b16 v[214:215], v228 offset:46592
	s_setprio 2
	v_mfma_f32_32x32x16_bf16 v[100:115], v[180:183], v[230:233], v[100:115]
	v_exp_f32_e32 v132, v132
	v_exp_f32_e32 v133, v133
	s_waitcnt lgkmcnt(12)
	v_mfma_f32_32x32x16_bf16 v[100:115], v[184:187], v[234:237], v[100:115]
	v_exp_f32_e32 v134, v134
	v_exp_f32_e32 v135, v135
	v_add_f32_e32 v178, v178, v132
	v_add_f32_e32 v179, v179, v133
	v_cvt_pk_bf16_f32 v238, v132, v133
	s_waitcnt lgkmcnt(10)
	v_mfma_f32_32x32x16_bf16 v[68:83], v[188:191], v[230:233], v[68:83]
	v_exp_f32_e32 v136, v136
	v_exp_f32_e32 v137, v137
	v_add_f32_e32 v178, v178, v134
	v_add_f32_e32 v179, v179, v135
	v_cvt_pk_bf16_f32 v239, v134, v135
	s_waitcnt lgkmcnt(8)
	v_mfma_f32_32x32x16_bf16 v[68:83], v[192:195], v[234:237], v[68:83]
	v_exp_f32_e32 v138, v138
	v_exp_f32_e32 v139, v139
	v_add_f32_e32 v178, v178, v136
	v_add_f32_e32 v179, v179, v137
	v_cvt_pk_bf16_f32 v240, v136, v137
	s_waitcnt lgkmcnt(6)
	v_mfma_f32_32x32x16_bf16 v[34:49], v[200:203], v[230:233], v[34:49]
	v_exp_f32_e32 v140, v140
	v_exp_f32_e32 v141, v141
	v_add_f32_e32 v178, v178, v138
	v_add_f32_e32 v179, v179, v139
	v_cvt_pk_bf16_f32 v241, v138, v139
	s_waitcnt lgkmcnt(4)
	v_mfma_f32_32x32x16_bf16 v[34:49], v[204:207], v[234:237], v[34:49]
	v_exp_f32_e32 v142, v142
	v_exp_f32_e32 v143, v143
	v_add_f32_e32 v178, v178, v140
	v_add_f32_e32 v179, v179, v141
	v_cvt_pk_bf16_f32 v242, v140, v141
	s_waitcnt lgkmcnt(2)
	v_mfma_f32_32x32x16_bf16 v[18:33], v[208:211], v[230:233], v[18:33]
	v_exp_f32_e32 v144, v144
	v_exp_f32_e32 v145, v145
	v_add_f32_e32 v178, v178, v142
	v_add_f32_e32 v179, v179, v143
	v_cvt_pk_bf16_f32 v243, v142, v143
	s_waitcnt lgkmcnt(0)
	v_mfma_f32_32x32x16_bf16 v[18:33], v[212:215], v[234:237], v[18:33]
	v_exp_f32_e32 v146, v146
	v_exp_f32_e32 v147, v147
	v_add_f32_e32 v178, v178, v144
	v_add_f32_e32 v179, v179, v145
	v_cvt_pk_bf16_f32 v244, v144, v145
	s_nop 0
	v_add_f32_e32 v178, v178, v146
	v_add_f32_e32 v179, v179, v147
	v_cvt_pk_bf16_f32 v245, v146, v147
	v_mfma_f32_32x32x16_bf16 v[116:131], v[180:183], v[238:241], v[116:131]
	v_mfma_f32_32x32x16_bf16 v[116:131], v[184:187], v[242:245], v[116:131]
	ds_read_b128 v[180:183], v250 offset:8192
	ds_read_b128 v[184:187], v219 offset:4096
	v_mfma_f32_32x32x16_bf16 v[84:99], v[188:191], v[238:241], v[84:99]
	v_mfma_f32_32x32x16_bf16 v[84:99], v[192:195], v[242:245], v[84:99]
	ds_read_b128 v[188:191], v246 offset:8192
	ds_read_b128 v[192:195], v219
	v_mfma_f32_32x32x16_bf16 v[50:65], v[200:203], v[238:241], v[50:65]
	v_mfma_f32_32x32x16_bf16 v[50:65], v[204:207], v[242:245], v[50:65]
	ds_read_b128 v[200:203], v247 offset:8192
	ds_read_b128 v[204:207], v219 offset:1024
	v_mfma_f32_32x32x16_bf16 v[2:17], v[208:211], v[238:241], v[2:17]
	v_mfma_f32_32x32x16_bf16 v[2:17], v[212:215], v[242:245], v[2:17]
	ds_read_b128 v[208:211], v248 offset:8192
	ds_read_b128 v[212:215], v219 offset:2048
	s_setprio 0
	v_add3_u32 v148, s20, v216, 32
	v_sub_u32_e32 v148, v148, v166
	v_cvt_f32_i32_e32 v148, v148
	v_mul_f32_e32 v148, v164, v148
	v_add_f32_e32 v149, v164, v148
	v_add_f32_e32 v150, v164, v149
	v_add_f32_e32 v151, v164, v150
	v_add_f32_e32 v152, v223, v151
	v_add_f32_e32 v153, v164, v152
	v_add_f32_e32 v154, v164, v153
	v_add_f32_e32 v155, v164, v154
	v_add_f32_e32 v156, v223, v155
	v_add_f32_e32 v157, v164, v156
	v_add_f32_e32 v158, v164, v157
	v_add_f32_e32 v159, v164, v158
	v_add_f32_e32 v160, v223, v159
	v_add_f32_e32 v161, v164, v160
	v_add_f32_e32 v162, v164, v161
	v_add_f32_e32 v163, v164, v162
	v_sub_f32_e64 v148, -|v148|, v221
	v_sub_f32_e64 v149, -|v149|, v221
	v_sub_f32_e64 v150, -|v150|, v221
	v_sub_f32_e64 v151, -|v151|, v221
	v_sub_f32_e64 v152, -|v152|, v221
	v_sub_f32_e64 v153, -|v153|, v221
	v_sub_f32_e64 v154, -|v154|, v221
	v_sub_f32_e64 v155, -|v155|, v221
	v_sub_f32_e64 v156, -|v156|, v221
	v_sub_f32_e64 v157, -|v157|, v221
	v_sub_f32_e64 v158, -|v158|, v221
	v_sub_f32_e64 v159, -|v159|, v221
	v_sub_f32_e64 v160, -|v160|, v221
	v_sub_f32_e64 v161, -|v161|, v221
	v_sub_f32_e64 v162, -|v162|, v221
	v_sub_f32_e64 v163, -|v163|, v221
	s_nop 1
	s_waitcnt lgkmcnt(6)
	v_mfma_f32_32x32x16_bf16 v[132:147], v[180:183], v[184:187], v[148:163]
	ds_read_b128 v[180:183], v249 offset:8192
	ds_read_b128 v[184:187], v219 offset:3072
	s_waitcnt lgkmcnt(6)
	v_mfma_f32_32x32x16_bf16 v[148:163], v[188:191], v[192:195], v[148:163]
	ds_read_b128 v[188:191], v251 offset:8192
	ds_read_b128 v[192:195], v219 offset:5120
	s_waitcnt lgkmcnt(6)
	v_mfma_f32_32x32x16_bf16 v[148:163], v[200:203], v[204:207], v[148:163]
	ds_read_b128 v[200:203], v252 offset:8192
	ds_read_b128 v[204:207], v219 offset:6144
	s_waitcnt lgkmcnt(6)
	v_mfma_f32_32x32x16_bf16 v[148:163], v[208:211], v[212:215], v[148:163]
	ds_read_b128 v[208:211], v253 offset:8192
	ds_read_b128 v[212:215], v219 offset:7168
	s_waitcnt lgkmcnt(6)
	v_mfma_f32_32x32x16_bf16 v[148:163], v[180:183], v[184:187], v[148:163]
	ds_read_b64_tr_b16 v[180:181], v228 offset:34816
	ds_read_b64_tr_b16 v[182:183], v228 offset:35328
	ds_read_b64_tr_b16 v[184:185], v228 offset:35840
	ds_read_b64_tr_b16 v[186:187], v228 offset:36352
	s_waitcnt lgkmcnt(8)
	v_mfma_f32_32x32x16_bf16 v[132:147], v[188:191], v[192:195], v[132:147]
	ds_read_b64_tr_b16 v[188:189], v228 offset:38912
	ds_read_b64_tr_b16 v[190:191], v228 offset:39424
	ds_read_b64_tr_b16 v[192:193], v228 offset:39936
	ds_read_b64_tr_b16 v[194:195], v228 offset:40448
	s_waitcnt lgkmcnt(10)
	v_mfma_f32_32x32x16_bf16 v[132:147], v[200:203], v[204:207], v[132:147]
	ds_read_b64_tr_b16 v[200:201], v228 offset:43008
	ds_read_b64_tr_b16 v[202:203], v228 offset:43520
	ds_read_b64_tr_b16 v[204:205], v228 offset:44032
	ds_read_b64_tr_b16 v[206:207], v228 offset:44544
	s_waitcnt lgkmcnt(12)
	v_mfma_f32_32x32x16_bf16 v[132:147], v[208:211], v[212:215], v[132:147]
	ds_read_b64_tr_b16 v[208:209], v228 offset:47104
	ds_read_b64_tr_b16 v[210:211], v228 offset:47616
	v_exp_f32_e32 v148, v148
	v_exp_f32_e32 v149, v149
	v_exp_f32_e32 v150, v150
	v_exp_f32_e32 v151, v151
	v_exp_f32_e32 v152, v152
	v_exp_f32_e32 v153, v153
	v_exp_f32_e32 v154, v154
	v_exp_f32_e32 v155, v155
	v_exp_f32_e32 v156, v156
	v_exp_f32_e32 v157, v157
	v_exp_f32_e32 v158, v158
	v_exp_f32_e32 v159, v159
	v_exp_f32_e32 v160, v160
	v_exp_f32_e32 v161, v161
	v_exp_f32_e32 v162, v162
	v_exp_f32_e32 v163, v163
	v_add_f32_e32 v170, v170, v148
	v_add_f32_e32 v171, v171, v149
	v_cvt_pk_bf16_f32 v230, v148, v149
	v_add_f32_e32 v170, v170, v150
	v_add_f32_e32 v171, v171, v151
	v_cvt_pk_bf16_f32 v231, v150, v151
	v_add_f32_e32 v170, v170, v152
	v_add_f32_e32 v171, v171, v153
	v_cvt_pk_bf16_f32 v232, v152, v153
	v_add_f32_e32 v170, v170, v154
	v_add_f32_e32 v171, v171, v155
	v_cvt_pk_bf16_f32 v233, v154, v155
	v_add_f32_e32 v170, v170, v156
	v_add_f32_e32 v171, v171, v157
	v_cvt_pk_bf16_f32 v234, v156, v157
	v_add_f32_e32 v170, v170, v158
	v_add_f32_e32 v171, v171, v159
	v_cvt_pk_bf16_f32 v235, v158, v159
	v_add_f32_e32 v170, v170, v160
	v_add_f32_e32 v171, v171, v161
	v_cvt_pk_bf16_f32 v236, v160, v161
	v_add_f32_e32 v170, v170, v162
	v_add_f32_e32 v171, v171, v163
	v_cvt_pk_bf16_f32 v237, v162, v163
	s_waitcnt lgkmcnt(12)
	ds_read_b64_tr_b16 v[212:213], v228 offset:48128
	ds_read_b64_tr_b16 v[214:215], v228 offset:48640
	s_cmp_le_i32 s12, 1
	s_cbranch_scc1 .Latt_first_b
	s_setprio 2
	v_mfma_f32_32x32x16_bf16 v[100:115], v[180:183], v[230:233], v[100:115]
	v_exp_f32_e32 v132, v132
	v_exp_f32_e32 v133, v133
	s_waitcnt lgkmcnt(12)
	v_mfma_f32_32x32x16_bf16 v[100:115], v[184:187], v[234:237], v[100:115]
	v_exp_f32_e32 v134, v134
	v_exp_f32_e32 v135, v135
	v_add_f32_e32 v178, v178, v132
	v_add_f32_e32 v179, v179, v133
	v_cvt_pk_bf16_f32 v238, v132, v133
	s_waitcnt lgkmcnt(10)
	v_mfma_f32_32x32x16_bf16 v[68:83], v[188:191], v[230:233], v[68:83]
	v_exp_f32_e32 v136, v136
	v_exp_f32_e32 v137, v137
	v_add_f32_e32 v178, v178, v134
	v_add_f32_e32 v179, v179, v135
	v_cvt_pk_bf16_f32 v239, v134, v135
	s_waitcnt lgkmcnt(8)
	v_mfma_f32_32x32x16_bf16 v[68:83], v[192:195], v[234:237], v[68:83]
	v_exp_f32_e32 v138, v138
	v_exp_f32_e32 v139, v139
	v_add_f32_e32 v178, v178, v136
	v_add_f32_e32 v179, v179, v137
	v_cvt_pk_bf16_f32 v240, v136, v137
	s_waitcnt lgkmcnt(6)
	v_mfma_f32_32x32x16_bf16 v[34:49], v[200:203], v[230:233], v[34:49]
	v_exp_f32_e32 v140, v140
	v_exp_f32_e32 v141, v141
	v_add_f32_e32 v178, v178, v138
	v_add_f32_e32 v179, v179, v139
	v_cvt_pk_bf16_f32 v241, v138, v139
	s_waitcnt lgkmcnt(4)
	v_mfma_f32_32x32x16_bf16 v[34:49], v[204:207], v[234:237], v[34:49]
	v_exp_f32_e32 v142, v142
	v_exp_f32_e32 v143, v143
	v_add_f32_e32 v178, v178, v140
	v_add_f32_e32 v179, v179, v141
	v_cvt_pk_bf16_f32 v242, v140, v141
	s_waitcnt lgkmcnt(2)
	v_mfma_f32_32x32x16_bf16 v[18:33], v[208:211], v[230:233], v[18:33]
	v_exp_f32_e32 v144, v144
	v_exp_f32_e32 v145, v145
	v_add_f32_e32 v178, v178, v142
	v_add_f32_e32 v179, v179, v143
	v_cvt_pk_bf16_f32 v243, v142, v143
	s_waitcnt lgkmcnt(0)
	v_mfma_f32_32x32x16_bf16 v[18:33], v[212:215], v[234:237], v[18:33]
	v_exp_f32_e32 v146, v146
	v_exp_f32_e32 v147, v147
	v_add_f32_e32 v178, v178, v144
	v_add_f32_e32 v179, v179, v145
	v_cvt_pk_bf16_f32 v244, v144, v145
	s_nop 0
	v_add_f32_e32 v178, v178, v146
	v_add_f32_e32 v179, v179, v147
	v_cvt_pk_bf16_f32 v245, v146, v147
	s_cmp_ge_i32 s13, s77
	s_cbranch_scc1 .Latt_fa_flush
	s_cmp_eq_u32 s13, s78
	s_cbranch_scc1 .Latt_fa_flush
	s_mov_b32 s101, 1
	s_branch .LBB0_981

.Latt_first_b:
	s_cmp_ge_i32 s13, s77
	s_cbranch_scc1 .Latt_fb_flush
	s_cmp_eq_u32 s13, s78
	s_cbranch_scc1 .Latt_fb_flush
	s_mov_b32 s101, 1
	s_branch .LBB0_981
